# compress MLP K-loop: each wave loads and converts one of the 8 x-fragments per group and shares it through a double-buffered LDS slab (8x fewer redundant L1 lookups and conversions)
# speedup vs baseline: 1.0178x; 1.0084x over previous
.LBB0_85:
	s_or_b64 exec, exec, s[12:13]
	s_lshl_b32 s12, s4, 4
	s_lshl_b32 s5, s4, 3
	v_and_b32_e32 v35, 15, v4
	s_and_b32 s12, s12, 0xf0
	s_and_b32 s15, s5, 0x180
	v_or_b32_e32 v2, s12, v35
	s_movk_i32 s2, 0xff
	s_lshl_b32 s18, s10, 9
	v_lshlrev_b32_e32 v3, 4, v2
	v_cmp_ne_u32_e32 vcc, s2, v2
	v_mov_b32_e32 v2, 0xfe0
	s_or_b32 s18, s18, s15
	s_bfe_u32 s13, s4, 0x20006
	v_cndmask_b32_e32 v2, v2, v3, vcc
	s_ashr_i32 s19, s18, 31
	v_readlane_b32 s20, v254, 46
	s_lshr_b32 s14, s4, 4
	s_lshr_b32 s5, s4, 6
	s_lshl_b64 s[16:17], s[10:11], 20
	v_lshl_or_b32 v2, s13, 12, v2
	s_lshl_b64 s[18:19], s[18:19], 1
	v_readlane_b32 s22, v254, 48
	v_mul_u32_u24_e32 v2, 0x1400, v2
	v_readlane_b32 s23, v254, 49
	s_add_u32 s18, s22, s18
	v_ashrrev_i32_e32 v5, 2, v4
	v_lshlrev_b32_e32 v2, 1, v2
	v_mov_b32_e32 v3, v0
	s_addc_u32 s19, s23, s19
	v_lshl_add_u64 v[8:9], s[18:19], 0, v[2:3]
	v_bfi_b32 v2, -16, v5, v4
	v_readlane_b32 s2, v254, 28
	v_ashrrev_i32_e32 v3, 31, v2
	s_add_u32 s16, s2, s16
	v_readlane_b32 s2, v254, 29
	v_lshlrev_b64 v[2:3], 13, v[2:3]
	s_addc_u32 s17, s2, s17
	v_bfe_u32 v1, v4, 4, 2
	v_lshl_add_u64 v[10:11], s[16:17], 0, v[2:3]
	v_mov_b32_e32 v2, 0
	v_lshlrev_b32_e32 v14, 3, v1
	v_and_b32_e32 v34, -16, v5
	v_lshl_add_u32 v15, v1, 5, 0
	v_lshlrev_b32_e32 v6, 4, v1
	v_mov_b32_e32 v7, v0
	s_mov_b32 s15, 0
	v_mov_b32_e32 v3, v2
	v_mov_b32_e32 v4, v2
	v_mov_b32_e32 v5, v2
	s_waitcnt lgkmcnt(0)
	s_barrier
	v_readlane_b32 s21, v254, 47
	v_lshrrev_b32_e32 v144, 6, v214
	v_lshlrev_b32_e32 v145, 7, v144
	v_lshlrev_b32_e32 v147, 4, v217
	v_lshl_add_u32 v146, v144, 10, v147
	v_add_u32_e32 v146, 0x8000, v146
	v_add_u32_e32 v147, 0x8000, v147
	v_lshlrev_b32_e32 v148, 6, v144
	v_mov_b32_e32 v149, 0x2700
	v_cmp_gt_u32_e32 vcc, 4, v144
	s_nop 1
	v_cndmask_b32_e32 v149, v149, v0, vcc
	v_add_u32_e32 v144, v148, v149
	v_lshl_add_u64 v[12:13], v[8:9], 0, v[6:7]
	v_add_co_u32_e32 v28, vcc, 0x18691000, v12
	s_nop 1
	v_addc_co_u32_e32 v29, vcc, 0, v13, vcc
	s_nop 0
	v_add_co_u32_e32 v28, vcc, v28, v144
	s_nop 1
	v_addc_co_u32_e32 v29, vcc, 0, v29, vcc
	v_lshl_add_u64 v[30:31], v[10:11], 0, v[6:7]
	global_load_dwordx4 v[64:67], v[28:29], off
	global_load_dwordx4 v[96:99], v[30:31], off offset:-256
	global_load_dwordx4 v[100:103], v[30:31], off offset:-192
	global_load_dwordx4 v[104:107], v[30:31], off offset:-128
	global_load_dwordx4 v[108:111], v[30:31], off offset:-64
	global_load_dwordx4 v[112:115], v[30:31], off
	global_load_dwordx4 v[116:119], v[30:31], off offset:64
	global_load_dwordx4 v[120:123], v[30:31], off offset:128
	global_load_dwordx4 v[124:127], v[30:31], off offset:192
	s_mov_b64 s[16:17], 0x5000
	v_lshl_add_u64 v[8:9], v[8:9], 0, s[16:17]
	v_lshl_add_u64 v[10:11], v[10:11], 0, s[82:83]
.LBB0_86:
	v_lshl_add_u64 v[12:13], v[8:9], 0, v[6:7]
	v_add_co_u32_e32 v28, vcc, 0x18691000, v12
	s_nop 1
	v_addc_co_u32_e32 v29, vcc, 0, v13, vcc
	s_nop 0
	v_add_co_u32_e32 v28, vcc, v28, v144
	s_nop 1
	v_addc_co_u32_e32 v29, vcc, 0, v29, vcc
	v_lshl_add_u64 v[30:31], v[10:11], 0, v[6:7]
	global_load_dwordx4 v[164:167], v[28:29], off
	global_load_dwordx4 v[236:239], v[30:31], off offset:-256
	global_load_dwordx4 v[240:243], v[30:31], off offset:-192
	global_load_dwordx4 v[244:247], v[30:31], off offset:-128
	global_load_dwordx4 v[248:251], v[30:31], off offset:-64
	global_load_dwordx4 v[208:211], v[30:31], off
	global_load_dwordx4 v[220:223], v[30:31], off offset:64
	global_load_dwordx4 v[40:43], v[30:31], off offset:128
	global_load_dwordx4 v[44:47], v[30:31], off offset:192
	s_mov_b64 s[16:17], 0x5000
	v_lshl_add_u64 v[8:9], v[8:9], 0, s[16:17]
	v_lshl_add_u64 v[10:11], v[10:11], 0, s[82:83]
	v_add3_u32 v36, s15, v15, v145
	s_addk_i32 s15, 0x400
	ds_read_b128 v[128:131], v36
	ds_read_b128 v[132:135], v36 offset:16
	s_waitcnt vmcnt(17)
	v_lshlrev_b32_e32 v20, 16, v64
	v_and_b32_e32 v21, 0xffff0000, v64
	v_lshlrev_b32_e32 v22, 16, v65
	v_and_b32_e32 v23, 0xffff0000, v65
	v_lshlrev_b32_e32 v24, 16, v66
	v_and_b32_e32 v25, 0xffff0000, v66
	v_lshlrev_b32_e32 v26, 16, v67
	v_and_b32_e32 v27, 0xffff0000, v67
	s_waitcnt lgkmcnt(0)
	v_pk_add_f32 v[20:21], v[128:129], v[20:21]
	v_pk_add_f32 v[22:23], v[130:131], v[22:23]
	v_pk_add_f32 v[24:25], v[132:133], v[24:25]
	v_pk_add_f32 v[26:27], v[134:135], v[26:27]
	v_cvt_pk_bf16_f32 v16, v20, v21
	v_cvt_pk_bf16_f32 v17, v22, v23
	v_cvt_pk_bf16_f32 v18, v24, v25
	v_cvt_pk_bf16_f32 v19, v26, v27
	ds_write_b128 v146, v[16:19]
	s_waitcnt lgkmcnt(0)
	s_barrier
	ds_read_b128 v[68:71], v147
	ds_read_b128 v[72:75], v147 offset:1024
	ds_read_b128 v[76:79], v147 offset:2048
	s_waitcnt vmcnt(16) lgkmcnt(2)
	v_mfma_f32_16x16x32_bf16 v[2:5], v[96:99], v[68:71], v[2:5]
	ds_read_b128 v[68:71], v147 offset:3072
	s_waitcnt vmcnt(15) lgkmcnt(2)
	v_mfma_f32_16x16x32_bf16 v[2:5], v[100:103], v[72:75], v[2:5]
	ds_read_b128 v[72:75], v147 offset:4096
	s_waitcnt vmcnt(14) lgkmcnt(2)
	v_mfma_f32_16x16x32_bf16 v[2:5], v[104:107], v[76:79], v[2:5]
	ds_read_b128 v[76:79], v147 offset:5120
	s_waitcnt vmcnt(13) lgkmcnt(2)
	v_mfma_f32_16x16x32_bf16 v[2:5], v[108:111], v[68:71], v[2:5]
	ds_read_b128 v[68:71], v147 offset:6144
	s_waitcnt vmcnt(12) lgkmcnt(2)
	v_mfma_f32_16x16x32_bf16 v[2:5], v[112:115], v[72:75], v[2:5]
	ds_read_b128 v[72:75], v147 offset:7168
	s_waitcnt vmcnt(11) lgkmcnt(2)
	v_mfma_f32_16x16x32_bf16 v[2:5], v[116:119], v[76:79], v[2:5]
	s_waitcnt vmcnt(10) lgkmcnt(1)
	v_mfma_f32_16x16x32_bf16 v[2:5], v[120:123], v[68:71], v[2:5]
	s_waitcnt vmcnt(9) lgkmcnt(0)
	v_mfma_f32_16x16x32_bf16 v[2:5], v[124:127], v[72:75], v[2:5]
	s_cmpk_eq_i32 s15, 0x3c00
	s_cbranch_scc1 .Lmy_cmp_last
	v_lshl_add_u64 v[12:13], v[8:9], 0, v[6:7]
	v_add_co_u32_e32 v28, vcc, 0x18691000, v12
	s_nop 1
	v_addc_co_u32_e32 v29, vcc, 0, v13, vcc
	s_nop 0
	v_add_co_u32_e32 v28, vcc, v28, v144
	s_nop 1
	v_addc_co_u32_e32 v29, vcc, 0, v29, vcc
	v_lshl_add_u64 v[30:31], v[10:11], 0, v[6:7]
	global_load_dwordx4 v[64:67], v[28:29], off
	global_load_dwordx4 v[96:99], v[30:31], off offset:-256
	global_load_dwordx4 v[100:103], v[30:31], off offset:-192
	global_load_dwordx4 v[104:107], v[30:31], off offset:-128
	global_load_dwordx4 v[108:111], v[30:31], off offset:-64
	global_load_dwordx4 v[112:115], v[30:31], off
	global_load_dwordx4 v[116:119], v[30:31], off offset:64
	global_load_dwordx4 v[120:123], v[30:31], off offset:128
	global_load_dwordx4 v[124:127], v[30:31], off offset:192
	s_mov_b64 s[16:17], 0x5000
	v_lshl_add_u64 v[8:9], v[8:9], 0, s[16:17]
	v_lshl_add_u64 v[10:11], v[10:11], 0, s[82:83]
	s_branch .Lmy_cmp_cont

.Lmy_cmp_cont:
	v_add3_u32 v36, s15, v15, v145
	s_addk_i32 s15, 0x400
	ds_read_b128 v[128:131], v36
	ds_read_b128 v[132:135], v36 offset:16
	s_waitcnt vmcnt(17)
	v_lshlrev_b32_e32 v20, 16, v164
	v_and_b32_e32 v21, 0xffff0000, v164
	v_lshlrev_b32_e32 v22, 16, v165
	v_and_b32_e32 v23, 0xffff0000, v165
	v_lshlrev_b32_e32 v24, 16, v166
	v_and_b32_e32 v25, 0xffff0000, v166
	v_lshlrev_b32_e32 v26, 16, v167
	v_and_b32_e32 v27, 0xffff0000, v167
	s_waitcnt lgkmcnt(0)
	v_pk_add_f32 v[20:21], v[128:129], v[20:21]
	v_pk_add_f32 v[22:23], v[130:131], v[22:23]
	v_pk_add_f32 v[24:25], v[132:133], v[24:25]
	v_pk_add_f32 v[26:27], v[134:135], v[26:27]
	v_cvt_pk_bf16_f32 v16, v20, v21
	v_cvt_pk_bf16_f32 v17, v22, v23
	v_cvt_pk_bf16_f32 v18, v24, v25
	v_cvt_pk_bf16_f32 v19, v26, v27
	ds_write_b128 v146, v[16:19] offset:8192
	s_waitcnt lgkmcnt(0)
	s_barrier
	ds_read_b128 v[68:71], v147 offset:8192
	ds_read_b128 v[72:75], v147 offset:9216
	ds_read_b128 v[76:79], v147 offset:10240
	s_waitcnt vmcnt(16) lgkmcnt(2)
	v_mfma_f32_16x16x32_bf16 v[2:5], v[236:239], v[68:71], v[2:5]
	ds_read_b128 v[68:71], v147 offset:11264
	s_waitcnt vmcnt(15) lgkmcnt(2)
	v_mfma_f32_16x16x32_bf16 v[2:5], v[240:243], v[72:75], v[2:5]
	ds_read_b128 v[72:75], v147 offset:12288
	s_waitcnt vmcnt(14) lgkmcnt(2)
	v_mfma_f32_16x16x32_bf16 v[2:5], v[244:247], v[76:79], v[2:5]
	ds_read_b128 v[76:79], v147 offset:13312
	s_waitcnt vmcnt(13) lgkmcnt(2)
	v_mfma_f32_16x16x32_bf16 v[2:5], v[248:251], v[68:71], v[2:5]
	ds_read_b128 v[68:71], v147 offset:14336
	s_waitcnt vmcnt(12) lgkmcnt(2)
	v_mfma_f32_16x16x32_bf16 v[2:5], v[208:211], v[72:75], v[2:5]
	ds_read_b128 v[72:75], v147 offset:15360
	s_waitcnt vmcnt(11) lgkmcnt(2)
	v_mfma_f32_16x16x32_bf16 v[2:5], v[220:223], v[76:79], v[2:5]
	s_waitcnt vmcnt(10) lgkmcnt(1)
	v_mfma_f32_16x16x32_bf16 v[2:5], v[40:43], v[68:71], v[2:5]
	s_waitcnt vmcnt(9) lgkmcnt(0)
	v_mfma_f32_16x16x32_bf16 v[2:5], v[44:47], v[72:75], v[2:5]
	s_cmpk_eq_i32 s15, 0x4000
	s_cbranch_scc0 .LBB0_86
	s_branch .Lmy_pad_cmp
.Lmy_tramp4:
	s_branch .LBB0_4
	s_nop 0
	s_nop 0
	s_nop 0
	s_nop 0
	s_nop 0
	s_nop 0
	s_nop 0
	s_nop 0
	s_nop 0
	s_nop 0
	s_nop 0
	s_nop 0
	s_nop 0
	s_nop 0
	s_nop 0
	s_nop 0
	s_nop 0
	s_nop 0
	s_nop 0
	s_nop 0
	s_nop 0
	s_nop 0
	s_nop 0
	s_nop 0
	s_nop 0
	s_nop 0
	s_nop 0
	s_nop 0
	s_nop 0
	s_nop 0
	s_nop 0
	s_nop 0
	s_nop 0
	s_nop 0
	s_nop 0
	s_nop 0
	s_nop 0
	s_nop 0
	s_nop 0
	s_nop 0
	s_nop 0
	s_nop 0
	s_nop 0
	s_nop 0
	s_nop 0
	s_nop 0
	s_nop 0
	s_nop 0
	s_nop 0
	s_nop 0
	s_nop 0
	s_nop 0
	s_nop 0
	s_nop 0
	s_nop 0
	s_nop 0
	s_nop 0
	s_nop 0
	s_nop 0
	s_nop 0
	s_nop 0
	s_nop 0
	s_nop 0
	s_nop 0
	s_nop 0
	s_nop 0
	s_nop 0
	s_nop 0
	s_nop 0
	s_nop 0
	s_nop 0
	s_nop 0
	s_nop 0
	s_nop 0
	s_nop 0
	s_nop 0
	s_nop 0
	s_nop 0
	s_nop 0
	s_nop 0
	s_nop 0
	s_nop 0
	s_nop 0
	s_nop 0
	s_nop 0
	s_nop 0
	s_nop 0
	s_nop 0
	s_nop 0
	s_nop 0
	s_nop 0
	s_nop 0
	s_nop 0
	s_nop 0
	s_nop 0
	s_nop 0
	s_nop 0
	s_nop 0
	s_nop 0
	s_nop 0
	s_nop 0
	s_nop 0
	s_nop 0
	s_nop 0
	s_nop 0
	s_nop 0
	s_nop 0
	s_nop 0
	s_nop 0
	s_nop 0
	s_nop 0
	s_nop 0
	s_nop 0
	s_nop 0
	s_nop 0
	s_nop 0
	s_nop 0
	s_nop 0
	s_nop 0
	s_nop 0
	s_nop 0
	s_nop 0
	s_nop 0
	s_nop 0
	s_nop 0
	s_nop 0
	s_nop 0
	s_nop 0
	s_nop 0
	s_nop 0
	s_nop 0
	s_nop 0
	s_nop 0
	s_nop 0
	s_nop 0
	s_nop 0
	s_nop 0
	s_nop 0
	s_nop 0
	s_nop 0
	s_nop 0
	s_nop 0
	s_nop 0
	s_nop 0
	s_nop 0
	s_nop 0
	s_nop 0
	s_nop 0
	s_nop 0
	s_nop 0
	s_nop 0
	s_nop 0
	s_nop 0
	s_nop 0
	s_nop 0
	s_nop 0
	s_nop 0
	s_nop 0
	s_nop 0
	s_nop 0
	s_nop 0
	s_nop 0
	s_nop 0
	s_nop 0
	s_nop 0
	s_nop 0
	s_nop 0
	s_nop 0
	s_nop 0
	s_nop 0
	s_nop 0
	s_nop 0
	s_nop 0
	s_nop 0
	s_nop 0
	s_nop 0
	s_nop 0
	s_nop 0
	s_nop 0
	s_nop 0
	s_nop 0
	s_nop 0
	s_nop 0
	s_nop 0
	s_nop 0
	s_nop 0
	s_nop 0
	s_nop 0
	s_nop 0
	s_nop 0
	s_nop 0
	s_nop 0
	s_nop 0
	s_nop 0
	s_nop 0
	s_nop 0
	s_nop 0
	s_nop 0
	s_nop 0
	s_nop 0
	s_nop 0
	s_nop 0
	s_nop 0
	s_nop 0
	s_nop 0
	s_nop 0
	s_nop 0
	s_nop 0
	s_nop 0
	s_nop 0
	s_nop 0
	s_nop 0
	s_nop 0
	s_nop 0
	s_nop 0
	s_nop 0
	s_nop 0
	s_nop 0
	s_nop 0
	s_nop 0
	s_nop 0
	s_nop 0
	s_nop 0
	s_nop 0
	s_nop 0
	s_nop 0
	s_nop 0
	s_nop 0
	s_nop 0
	s_nop 0
	s_nop 0
	s_nop 0
	s_nop 0
	s_nop 0
	s_nop 0
	s_nop 0
	s_nop 0
	s_nop 0
	s_nop 0
	s_nop 0
	s_nop 0
	s_nop 0
	s_nop 0
	s_nop 0
	s_nop 0
	s_nop 0
	s_nop 0
	s_nop 0
	s_nop 0
	s_nop 0
	s_nop 0
	s_nop 0
	s_nop 0
	s_nop 0
	s_nop 0
	s_nop 0
	s_nop 0
	s_nop 0
	s_nop 0
	s_nop 0
	s_nop 0
	s_nop 0
	s_nop 0
	s_nop 0
	s_nop 0
	s_nop 0
	s_nop 0
	s_nop 0
	s_nop 0
	s_nop 0
	s_nop 0
	s_nop 0
	s_nop 0
	s_nop 0
	s_nop 0
	s_nop 0
	s_nop 0
	s_nop 0
	s_nop 0
	s_nop 0
	s_nop 0
	s_nop 0
	s_nop 0
	s_nop 0
	s_nop 0
	s_nop 0
	s_nop 0
	s_nop 0
	s_nop 0
	s_nop 0
	s_nop 0
	s_nop 0
	s_nop 0
	s_nop 0
	s_nop 0
	s_nop 0
	s_nop 0
	s_nop 0
	s_nop 0
	s_nop 0
	s_nop 0
	s_nop 0
	s_nop 0
	s_nop 0
	s_nop 0
	s_nop 0
	s_nop 0
	s_nop 0
	s_nop 0
	s_nop 0
	s_nop 0
	s_nop 0
	s_nop 0
	s_nop 0
	s_nop 0
	s_nop 0
	s_nop 0
	s_nop 0
	s_nop 0
	s_nop 0
	s_nop 0
	s_nop 0
	s_nop 0
	s_nop 0
	s_nop 0
	s_nop 0
	s_nop 0
	s_nop 0
	s_nop 0
	s_nop 0
	s_nop 0
	s_nop 0
	s_nop 0
	s_nop 0
	s_nop 0
	s_nop 0
	s_nop 0
	s_nop 0
	s_nop 0
	s_nop 0
	s_nop 0
	s_nop 0
	s_nop 0
	s_nop 0
	s_nop 0
	s_nop 0
	s_nop 0
	s_nop 0
	s_nop 0
	s_nop 0
	s_nop 0
	s_nop 0
	s_nop 0
	s_nop 0
	s_nop 0
	s_nop 0
	s_nop 0
	s_nop 0
	s_nop 0
	s_nop 0
	s_nop 0
	s_nop 0
	s_nop 0
	s_nop 0
	s_nop 0
	s_nop 0
	s_nop 0
	s_nop 0
	s_nop 0
	s_nop 0
	s_nop 0
	s_nop 0
	s_nop 0
	s_nop 0
	s_nop 0
	s_nop 0
	s_nop 0
	s_nop 0
	s_nop 0
	s_nop 0
	s_nop 0
	s_nop 0
	s_nop 0
	s_nop 0
	s_nop 0
	s_nop 0
	s_nop 0
	s_nop 0
	s_nop 0
	s_nop 0
	s_nop 0
	s_nop 0
	s_nop 0
	s_nop 0
	s_nop 0
	s_nop 0
	s_nop 0
	s_nop 0
	s_nop 0
	s_nop 0
	s_nop 0
	s_nop 0
	s_nop 0
	s_nop 0
	s_nop 0
	s_nop 0
	s_nop 0
	s_nop 0
	s_nop 0
	s_nop 0
	s_nop 0
	s_nop 0
	s_nop 0
	s_nop 0
	s_nop 0
	s_nop 0
	s_nop 0
	s_nop 0
	s_nop 0
	s_nop 0
	s_nop 0
	s_nop 0
	s_nop 0
	s_nop 0
	s_nop 0
	s_nop 0
	s_nop 0
	s_nop 0
	s_nop 0
	s_nop 0
	s_nop 0
	s_nop 0
	s_nop 0
	s_nop 0
	s_nop 0
	s_nop 0
	s_nop 0
	s_nop 0
	s_nop 0
	s_nop 0
	s_nop 0
	s_nop 0
	s_nop 0
	s_nop 0
	s_nop 0
	s_nop 0
	s_nop 0
	s_nop 0
	s_nop 0
	s_nop 0
	s_nop 0
	s_nop 0
	s_nop 0
	s_nop 0
	s_nop 0
	s_nop 0
	s_nop 0
	s_nop 0
	s_nop 0
	s_nop 0
	s_nop 0
	s_nop 0
	s_nop 0
	s_nop 0
	s_nop 0
	s_nop 0
	s_nop 0
	s_nop 0
	s_nop 0
	s_nop 0
	s_nop 0
	s_nop 0
	s_nop 0
	s_nop 0
	s_nop 0
	s_nop 0
	s_nop 0
	s_nop 0
	s_nop 0
	s_nop 0
	s_nop 0
	s_nop 0
	s_nop 0
	s_nop 0
	s_nop 0
	s_nop 0
	s_nop 0
	s_nop 0
	s_nop 0
	s_nop 0
	s_nop 0
	s_nop 0
	s_nop 0
	s_nop 0
	s_nop 0
	s_nop 0
	s_nop 0
	s_nop 0
	s_nop 0
	s_nop 0
	s_nop 0
	s_nop 0
	s_nop 0
	s_nop 0
	s_nop 0
	s_nop 0
	s_nop 0
	s_nop 0
	s_nop 0
	s_nop 0
	s_nop 0
	s_nop 0
	s_nop 0
	s_nop 0
	s_nop 0
	s_nop 0
	s_nop 0
	s_nop 0
	s_nop 0
	s_nop 0
